# speedup vs baseline: 1.0212x; 1.0110x over previous
; __device__ __forceinline__ void phase_glax(const Params& P, char* shm, int l, int bid, int nb) {
;     ...
;   for (int u = bid; u < (P.tg / 64) * 4; u += nb) {
;     const int hd = u & 3;
;     if (hd != cur_hd) {
;       cur_hd = hd;
;       const float* wf = P.w_lr2_f + (long)l * 16 * 512 + hd * 128 + wid * 16 + fr;
;       const float* wb = P.w_lr2_b + (long)l * 16 * 512 + hd * 128 + wid * 16 + fr;
; #pragma unroll
;       for (int j = 0; j < 8; ++j) {
;         w2a0[j] = fq < 2 ? (short)f2bf(wf[((fq & 1) * 8 + j) * 512]) : (short)0;
;         w2a1[j] = fq < 2 ? (short)f2bf(wb[((fq & 1) * 8 + j) * 512]) : (short)0;
;       }
;       bias0 = P.b_lr_f[(long)l * 512 + hd * 128 + dk];
;       bias1 = P.b_lr_b[(long)l * 512 + hd * 128 + dk];
.LBB0_309:
	s_and_b32 s67, s96, 3
	s_cmp_lg_u32 s67, s8
	s_mov_b64 s[6:7], -1
	s_cbranch_scc0 .LBB0_343
	s_lshl_b32 s58, s67, 9
	v_lshl_add_u64 v[2:3], v[62:63], 0, s[58:59]
	v_mov_b32_e32 v6, 0
	v_lshlrev_b32_e32 v0, 2, v58
	v_mov_b32_e32 v7, 0
	s_and_saveexec_b64 s[6:7], s[4:5]
	s_cbranch_execz .LBB0_312
	v_lshl_add_u64 v[4:5], v[2:3], 0, v[0:1]
	global_load_dword v196, v[4:5], off
.LBB0_312:
	s_or_b64 exec, exec, s[6:7]
	s_lshl_b32 s58, s67, 7
	s_lshl_b32 s6, s58, 2
	s_mov_b32 s7, s59
	v_lshl_add_u64 v[4:5], v[64:65], 0, s[6:7]
	s_and_saveexec_b64 s[6:7], s[4:5]
	s_cbranch_execz .LBB0_314
	v_lshl_add_u64 v[8:9], v[4:5], 0, v[0:1]
	global_load_dword v197, v[8:9], off
.LBB0_314:
	s_or_b64 exec, exec, s[6:7]
	v_mov_b32_e32 v20, 0
	v_mov_b32_e32 v8, 0
	s_and_saveexec_b64 s[6:7], s[4:5]
	s_cbranch_execz .LBB0_316
	v_lshl_add_u64 v[8:9], v[2:3], 0, v[0:1]
	global_load_dword v198, v[8:9], off offset:2048
.LBB0_316:
	s_or_b64 exec, exec, s[6:7]
	s_and_saveexec_b64 s[6:7], s[4:5]
	s_cbranch_execz .LBB0_318
	v_lshl_add_u64 v[20:21], v[4:5], 0, v[0:1]
	global_load_dword v199, v[20:21], off offset:2048
.LBB0_318:
	s_or_b64 exec, exec, s[6:7]
	v_mov_b32_e32 v21, 0
	v_mov_b32_e32 v9, 0
	s_and_saveexec_b64 s[6:7], s[4:5]
	s_cbranch_execz .LBB0_320
	v_lshl_add_u64 v[22:23], v[2:3], 0, v[0:1]
	v_add_co_u32_e32 v22, vcc, 0x1000, v22
	s_nop 1
	v_addc_co_u32_e32 v23, vcc, 0, v23, vcc
	global_load_dword v200, v[22:23], off
.LBB0_320:
	s_or_b64 exec, exec, s[6:7]
	s_and_saveexec_b64 s[6:7], s[4:5]
	s_cbranch_execz .LBB0_322
	v_lshl_add_u64 v[22:23], v[4:5], 0, v[0:1]
	v_add_co_u32_e32 v22, vcc, 0x1000, v22
	s_nop 1
	v_addc_co_u32_e32 v23, vcc, 0, v23, vcc
	global_load_dword v201, v[22:23], off
.LBB0_322:
	s_or_b64 exec, exec, s[6:7]
	v_mov_b32_e32 v22, 0
	v_mov_b32_e32 v23, 0
	s_and_saveexec_b64 s[6:7], s[4:5]
	s_cbranch_execz .LBB0_324
	v_lshl_add_u64 v[24:25], v[2:3], 0, v[0:1]
	v_add_co_u32_e32 v24, vcc, 0x1000, v24
	s_nop 1
	v_addc_co_u32_e32 v25, vcc, 0, v25, vcc
	global_load_dword v202, v[24:25], off offset:2048
.LBB0_324:
	s_or_b64 exec, exec, s[6:7]
	s_and_saveexec_b64 s[6:7], s[4:5]
	s_cbranch_execz .LBB0_326
	v_lshl_add_u64 v[24:25], v[4:5], 0, v[0:1]
	v_add_co_u32_e32 v24, vcc, 0x1000, v24
	s_nop 1
	v_addc_co_u32_e32 v25, vcc, 0, v25, vcc
	global_load_dword v203, v[24:25], off offset:2048
.LBB0_326:
	s_or_b64 exec, exec, s[6:7]
	v_mov_b32_e32 v24, 0
	v_mov_b32_e32 v25, 0
	s_and_saveexec_b64 s[6:7], s[4:5]
	s_cbranch_execz .LBB0_328
	v_lshl_add_u64 v[26:27], v[2:3], 0, v[0:1]
	v_add_co_u32_e32 v26, vcc, 0x2000, v26
	s_nop 1
	v_addc_co_u32_e32 v27, vcc, 0, v27, vcc
	global_load_dword v204, v[26:27], off
.LBB0_328:
	s_or_b64 exec, exec, s[6:7]
	s_and_saveexec_b64 s[6:7], s[4:5]
	s_cbranch_execz .LBB0_330
	v_lshl_add_u64 v[26:27], v[4:5], 0, v[0:1]
	v_add_co_u32_e32 v26, vcc, 0x2000, v26
	s_nop 1
	v_addc_co_u32_e32 v27, vcc, 0, v27, vcc
	global_load_dword v205, v[26:27], off
.LBB0_330:
	s_or_b64 exec, exec, s[6:7]
	v_mov_b32_e32 v26, 0
	v_mov_b32_e32 v27, 0
	s_and_saveexec_b64 s[6:7], s[4:5]
	s_cbranch_execz .LBB0_332
	v_lshl_add_u64 v[28:29], v[2:3], 0, v[0:1]
	v_add_co_u32_e32 v28, vcc, 0x2000, v28
	s_nop 1
	v_addc_co_u32_e32 v29, vcc, 0, v29, vcc
	global_load_dword v206, v[28:29], off offset:2048
.LBB0_332:
	s_or_b64 exec, exec, s[6:7]
	s_and_saveexec_b64 s[6:7], s[4:5]
	s_cbranch_execz .LBB0_334
	v_lshl_add_u64 v[28:29], v[4:5], 0, v[0:1]
	v_add_co_u32_e32 v28, vcc, 0x2000, v28
	s_nop 1
	v_addc_co_u32_e32 v29, vcc, 0, v29, vcc
	global_load_dword v207, v[28:29], off offset:2048
.LBB0_334:
	s_or_b64 exec, exec, s[6:7]
	v_mov_b32_e32 v28, 0
	v_mov_b32_e32 v29, 0
	s_and_saveexec_b64 s[6:7], s[4:5]
	s_cbranch_execz .LBB0_336
	v_lshl_add_u64 v[30:31], v[2:3], 0, v[0:1]
	v_add_co_u32_e32 v30, vcc, 0x3000, v30
	s_nop 1
	v_addc_co_u32_e32 v31, vcc, 0, v31, vcc
	global_load_dword v208, v[30:31], off
.LBB0_336:
	s_or_b64 exec, exec, s[6:7]
	s_and_saveexec_b64 s[6:7], s[4:5]
	s_cbranch_execz .LBB0_338
	v_lshl_add_u64 v[30:31], v[4:5], 0, v[0:1]
	v_add_co_u32_e32 v30, vcc, 0x3000, v30
	s_nop 1
	v_addc_co_u32_e32 v31, vcc, 0, v31, vcc
	global_load_dword v209, v[30:31], off
.LBB0_338:
	s_or_b64 exec, exec, s[6:7]
	v_mov_b32_e32 v30, 0
	v_mov_b32_e32 v31, 0
	s_and_saveexec_b64 s[6:7], s[4:5]
	s_cbranch_execz .LBB0_340
	v_lshl_add_u64 v[2:3], v[2:3], 0, v[0:1]
	v_add_co_u32_e32 v2, vcc, 0x3000, v2
	s_nop 1
	v_addc_co_u32_e32 v3, vcc, 0, v3, vcc
	global_load_dword v210, v[2:3], off offset:2048
.LBB0_340:
	s_or_b64 exec, exec, s[6:7]
	s_and_saveexec_b64 s[6:7], s[4:5]
	s_cbranch_execz .LBB0_342
	v_lshl_add_u64 v[2:3], v[4:5], 0, v[0:1]
	v_add_co_u32_e32 v2, vcc, 0x3000, v2
	s_nop 1
	v_addc_co_u32_e32 v3, vcc, 0, v3, vcc
	global_load_dword v211, v[2:3], off offset:2048
.LBB0_342:
	s_or_b64 exec, exec, s[6:7]
	s_and_saveexec_b64 s[6:7], s[4:5]
	s_waitcnt vmcnt(0)
	v_cvt_pk_bf16_f32 v7, v196, s0
	v_cvt_pk_bf16_f32 v6, v197, s0
	v_cvt_pk_bf16_f32 v8, v198, s0
	v_cvt_pk_bf16_f32 v20, v199, s0
	v_cvt_pk_bf16_f32 v9, v200, s0
	v_cvt_pk_bf16_f32 v21, v201, s0
	v_cvt_pk_bf16_f32 v23, v202, s0
	v_cvt_pk_bf16_f32 v22, v203, s0
	v_cvt_pk_bf16_f32 v25, v204, s0
	v_cvt_pk_bf16_f32 v24, v205, s0
	v_cvt_pk_bf16_f32 v27, v206, s0
	v_cvt_pk_bf16_f32 v26, v207, s0
	v_cvt_pk_bf16_f32 v29, v208, s0
	v_cvt_pk_bf16_f32 v28, v209, s0
	v_cvt_pk_bf16_f32 v31, v210, s0
	v_cvt_pk_bf16_f32 v30, v211, s0
	s_or_b64 exec, exec, s[6:7]
	v_or_b32_e32 v2, s58, v60
	v_mov_b32_e32 v3, v61
	v_readlane_b32 s12, v250, 12
	v_lshlrev_b64 v[2:3], 2, v[2:3]
	v_readlane_b32 s22, v250, 22
	v_readlane_b32 s23, v250, 23
	v_readlane_b32 s26, v250, 26
	v_readlane_b32 s27, v250, 27
	v_lshl_add_u64 v[4:5], s[22:23], 0, v[2:3]
	global_load_dword v59, v[4:5], off
	v_lshl_add_u64 v[2:3], s[26:27], 0, v[2:3]
	global_load_dword v104, v[2:3], off
	v_perm_b32 v5, v31, v29, s74
	v_perm_b32 v4, v27, v25, s74
	v_perm_b32 v3, v23, v9, s74
	v_perm_b32 v2, v8, v7, s74
	v_perm_b32 v9, v30, v28, s74
	v_perm_b32 v8, v26, v24, s74
	v_perm_b32 v7, v22, v21, s74
	v_perm_b32 v6, v20, v6, s74
	s_mov_b64 s[6:7], 0
	v_readlane_b32 s13, v250, 13
	v_readlane_b32 s14, v250, 14
	v_readlane_b32 s15, v250, 15
	v_readlane_b32 s16, v250, 16
	v_readlane_b32 s17, v250, 17
	v_readlane_b32 s18, v250, 18
	v_readlane_b32 s19, v250, 19
	v_readlane_b32 s20, v250, 20
	v_readlane_b32 s21, v250, 21
	v_readlane_b32 s24, v250, 24
	v_readlane_b32 s25, v250, 25

; __device__ __forceinline__ int prow(int c) { return (c & ~31) | (((c >> 2) & 1) << 4) | (((c >> 3) & 3) << 2) | (c & 3); }
; __device__ __forceinline__ void glax_item(char* shm, const Params& P, int l, int cgi, int hd, bf16x8 w2a0, bf16x8 w2a1,
;                                           float bias0, float bias1) {
;     ...
;   u16x8 qk[4];
; #pragma unroll
;   for (int k = 0; k < 2; ++k) {
;     const int u = tid + k * 512, row = u >> 4, c8 = (u & 15) * 8;
;     qk[k] = *(const u16x8*)(hb + (long)row * HS + C_Q + hd * 128 + c8);
;     qk[2 + k] = *(const u16x8*)(hb + (long)row * HS + C_K + hd * 128 + c8);
;   }
;   __syncthreads();
; #pragma unroll
;   for (int k = 0; k < 2; ++k) {
;     const int u = tid + k * 512, row = u >> 4, c8 = (u & 15) * 8;
;     *(u16x8*)(Q + row * 128 + c8) = qk[k];
;     *(u16x8*)(Q + 64 * 128 + row * 128 + c8) = qk[2 + k];
;   }
;   if (tid < 256) *(u16x8*)(LR + (tid >> 2) * 32 + (tid & 3) * 8) = *(const u16x8*)(hb + (long)(tid >> 2) * HS + C_LRF + (tid & 3) * 8);
; #pragma unroll
;   for (int k = 0; k < 4; ++k) {
;     int u = tid + k * 512, j = u >> 5, c8 = (u & 31) * 8;
;     u16x8 v = *(const u16x8*)(hb + (long)j * HS + C_V + hd * 256 + c8);
; #pragma unroll
;     for (int e = 0; e < 8; ++e) VT[prow(c8 + e) * JP + j] = v[e];
;   }
.LBB0_345:
	s_ashr_i32 s65, s96, 2
	s_lshl_b32 s10, s65, 6
	s_mul_i32 s6, s65, 0xb8000
	s_mul_hi_i32 s7, s10, 0x2e00
	s_add_u32 s6, s94, s6
	v_mov_b32_e32 v24, v182
	s_addc_u32 s7, s95, s7
	v_mov_b64_e32 v[14:15], s[6:7]
	v_ashrrev_i32_e32 v19, 4, v24
	v_lshlrev_b32_e32 v22, 3, v24
	v_mad_i64_i32 v[10:11], s[8:9], v19, s66, v[14:15]
	v_and_b32_e32 v25, 0x78, v22
	s_lshl_b64 s[8:9], s[58:59], 1
	v_lshl_add_u64 v[10:11], v[10:11], 0, s[8:9]
	v_lshlrev_b32_e32 v0, 1, v25
	v_lshl_add_u64 v[16:17], v[10:11], 0, v[0:1]
	v_add_u32_e32 v21, 0x200, v24
	global_load_dwordx4 v[10:13], v[16:17], off
	global_load_dwordx4 v[26:29], v[16:17], off offset:1024
	v_ashrrev_i32_e32 v17, 4, v21
	v_mad_i64_i32 v[14:15], s[12:13], v17, s66, v[14:15]
	v_lshl_add_u64 v[14:15], v[14:15], 0, s[8:9]
	v_lshl_add_u64 v[14:15], v[14:15], 0, v[0:1]
	global_load_dwordx4 v[30:33], v[14:15], off
	global_load_dwordx4 v[34:37], v[14:15], off offset:1024
	v_lshrrev_b32_e32 v216, 5, v24
	v_mul_u32_u24_e32 v216, s66, v216
	v_and_b32_e32 v217, 31, v24
	v_lshl_add_u32 v216, v217, 4, v216
	s_lshl_b32 s8, s67, 9
	v_add_u32_e32 v216, s8, v216
	global_load_dwordx4 v[196:199], v216, s[6:7] offset:2048
	v_add_u32_e32 v217, 0x2e000, v216
	global_load_dwordx4 v[200:203], v217, s[6:7] offset:2048
	v_add_u32_e32 v217, 0x5c000, v216
	global_load_dwordx4 v[204:207], v217, s[6:7] offset:2048
	v_add_u32_e32 v217, 0x8a000, v216
	global_load_dwordx4 v[208:211], v217, s[6:7] offset:2048
	v_lshrrev_b32_e32 v217, 2, v24
	v_mul_u32_u24_e32 v217, s66, v217
	v_and_b32_e32 v216, 3, v24
	v_lshl_add_u32 v217, v216, 4, v217
	v_add_u32_e32 v217, 0x2000, v217
	global_load_dwordx4 v[212:215], v217, s[6:7] offset:3072
	s_movk_i32 s8, 0x100
	v_lshlrev_b32_e32 v14, 4, v24
	v_cmp_gt_i32_e32 vcc, s8, v24
	s_movk_i32 s8, 0xff00
	v_and_or_b32 v14, v14, s8, v0
	s_waitcnt lgkmcnt(0)
	s_barrier
	s_waitcnt vmcnt(0)
	ds_write_b128 v14, v[10:13]
	ds_write_b128 v14, v[26:29] offset:16384
	ds_write_b128 v14, v[30:33] offset:8192
	ds_write_b128 v14, v[34:37] offset:24576
	v_lshlrev_b32_e32 v27, 1, v22
	s_and_saveexec_b64 s[8:9], vcc
	s_cbranch_execz .LBB0_347
	v_ashrrev_i32_e32 v16, 2, v24
	v_mov_b64_e32 v[10:11], s[6:7]
	v_mad_i64_i32 v[10:11], s[12:13], v16, s66, v[10:11]
	v_and_b32_e32 v14, 48, v27
	v_mov_b32_e32 v15, v1
	v_lshl_add_u64 v[10:11], v[10:11], 0, v[14:15]
	v_add_co_u32_e32 v10, vcc, 0x2000, v10
	v_lshl_or_b32 v14, v16, 6, v14
	s_nop 0
	v_addc_co_u32_e32 v11, vcc, 0, v11, vcc
	v_add_u32_e32 v14, 0x13c00, v14
	s_waitcnt lgkmcnt(0)
	ds_write_b128 v14, v[212:215]
.LBB0_347:
	s_or_b64 exec, exec, s[8:9]
	v_ashrrev_i32_e32 v18, 5, v24
	v_mov_b64_e32 v[14:15], s[6:7]
	v_and_b32_e32 v12, 0xf8, v22
	v_mad_i64_i32 v[10:11], s[6:7], v18, s66, v[14:15]
	s_lshl_b32 s58, s67, 9
	v_lshrrev_b32_e32 v13, 1, v22
	v_lshl_add_u64 v[10:11], v[10:11], 0, s[58:59]
	v_lshlrev_b32_e32 v30, 1, v12
	v_mov_b32_e32 v31, v1
	v_and_b32_e32 v12, 0xe0, v22
	v_lshl_add_u64 v[10:11], v[10:11], 0, v[30:31]
	v_and_or_b32 v12, v13, 12, v12
	v_mul_u32_u24_e32 v20, 0x90, v12
	v_bfe_u32 v216, v24, 2, 3
	v_bfe_u32 v217, v24, 5, 3
	v_lshl_add_u32 v217, v217, 1, v20
	v_lshrrev_b32_e32 v219, 8, v24
	v_xor_b32_e32 v220, v219, v216
	v_lshl_add_u32 v18, v220, 4, v217
	v_add_u32_e32 v70, 0x400, v24
	v_add_u32_e32 v74, 0x600, v24
	s_ashr_i32 s97, s96, 31
	v_readlane_b32 s8, v248, 3
	v_and_b32_e32 v16, 0x7f, v24
	v_readlane_b32 s9, v248, 4
	v_ashrrev_i32_e32 v26, 7, v24
	v_bfe_u32 v28, v24, 4, 2
	v_and_b32_e32 v23, 15, v24
	ds_write_b16 v18, v196 offset:34816
	ds_write_b16_d16_hi v18, v196 offset:34960
	ds_write_b16 v18, v197 offset:35104
	ds_write_b16_d16_hi v18, v197 offset:35248
	ds_write_b16 v18, v198 offset:37120
	ds_write_b16_d16_hi v18, v198 offset:37264
	ds_write_b16 v18, v199 offset:37408
	ds_write_b16_d16_hi v18, v199 offset:37552
	v_ashrrev_i32_e32 v12, 5, v21
	v_mad_i64_i32 v[10:11], s[6:7], v12, s66, v[14:15]
	v_lshl_add_u64 v[10:11], v[10:11], 0, s[58:59]
	v_lshl_add_u64 v[10:11], v[10:11], 0, v[30:31]
	v_or_b32_e32 v220, 2, v219
	v_xor_b32_e32 v220, v220, v216
	v_lshl_add_u32 v18, v220, 4, v217
	ds_write_b16 v18, v200 offset:34816
	ds_write_b16_d16_hi v18, v200 offset:34960
	ds_write_b16 v18, v201 offset:35104
	ds_write_b16_d16_hi v18, v201 offset:35248
	ds_write_b16 v18, v202 offset:37120
	ds_write_b16_d16_hi v18, v202 offset:37264
	ds_write_b16 v18, v203 offset:37408
	ds_write_b16_d16_hi v18, v203 offset:37552
	v_ashrrev_i32_e32 v12, 5, v70
	v_mad_i64_i32 v[10:11], s[6:7], v12, s66, v[14:15]
	v_lshl_add_u64 v[10:11], v[10:11], 0, s[58:59]
	v_lshl_add_u64 v[10:11], v[10:11], 0, v[30:31]
	v_or_b32_e32 v220, 4, v219
	v_xor_b32_e32 v220, v220, v216
	v_lshl_add_u32 v18, v220, 4, v217
	ds_write_b16 v18, v204 offset:34816
	ds_write_b16_d16_hi v18, v204 offset:34960
	ds_write_b16 v18, v205 offset:35104
	ds_write_b16_d16_hi v18, v205 offset:35248
	ds_write_b16 v18, v206 offset:37120
	ds_write_b16_d16_hi v18, v206 offset:37264
	ds_write_b16 v18, v207 offset:37408
	ds_write_b16_d16_hi v18, v207 offset:37552
	v_ashrrev_i32_e32 v12, 5, v74
	v_mad_i64_i32 v[10:11], s[6:7], v12, s66, v[14:15]
	v_lshl_add_u64 v[10:11], v[10:11], 0, s[58:59]
	v_lshl_add_u64 v[10:11], v[10:11], 0, v[30:31]
	v_or_b32_e32 v220, 6, v219
	v_xor_b32_e32 v220, v220, v216
	v_lshl_add_u32 v14, v220, 4, v217
	s_lshl_b64 s[6:7], s[96:97], 15
	s_add_u32 s6, s8, s6
	v_lshlrev_b32_e32 v18, 1, v16
	s_addc_u32 s7, s9, s7
	v_mov_b32_e32 v15, v1
	v_lshlrev_b32_e32 v20, 4, v28
	ds_write_b16 v14, v208 offset:34816
	ds_write_b16_d16_hi v14, v208 offset:34960
	ds_write_b16 v14, v209 offset:35104
	ds_write_b16_d16_hi v14, v209 offset:35248
	ds_write_b16 v14, v210 offset:37120
	ds_write_b16_d16_hi v14, v210 offset:37264
	ds_write_b16 v14, v211 offset:37408
	ds_write_b16_d16_hi v14, v211 offset:37552
	v_and_b32_e32 v14, 0x70, v27
	v_lshl_or_b32 v10, v26, 12, v18
	v_lshl_add_u64 v[66:67], s[6:7], 0, v[14:15]
	v_ashrrev_i32_e32 v15, 3, v24
	s_waitcnt lgkmcnt(0)
	s_barrier
; __device__ __forceinline__ int prow(int c) { return (c & ~31) | (((c >> 2) & 1) << 4) | (((c >> 3) & 3) << 2) | (c & 3); }
; __device__ __forceinline__ void glax_z(float* Z, const u16* LR, int dir, bf16x8 w2a, int wid, int fr, int fq) {
; #pragma unroll
;   for (int rt = 0; rt < 4; ++rt) {
;     bf16x8 b = bf16x8{0, 0, 0, 0, 0, 0, 0, 0};
;     if (fq < 2) b = *(const bf16x8*)(LR + (rt * 16 + fr) * 32 + dir * 16 + fq * 8);
;     f32x4 d = __builtin_amdgcn_mfma_f32_16x16x32_bf16(w2a, b, f32x4{0.f, 0.f, 0.f, 0.f}, 0, 0, 0);
;     *(f32x4*)(Z + (rt * 16 + fr) * ZP + wid * 16 + fq * 4) = d;
;   }
; __device__ __forceinline__ void glax_item(char* shm, const Params& P, int l, int cgi, int hd, bf16x8 w2a0, bf16x8 w2a1,
;                                           float bias0, float bias1) {
;     ...
;   u16 qraw[16], kraw[16];
; #pragma unroll
;   for (int rr = 0; rr < 16; ++rr) {
;     qraw[rr] = Q[(rg * 16 + rr) * 128 + dk];
;     kraw[rr] = Q[64 * 128 + (rg * 16 + rr) * 128 + dk];
;   }
;   {
;     u16* vtg = P.vtg + (long)(cgi * 4 + hd) * 256 * 64;
; #pragma unroll
;     for (int k = 0; k < 4; ++k) {
;       int u = tid + k * 512, dv = u >> 3, j8 = (u & 7) * 8;
;       *(u16x8*)(vtg + dv * 64 + j8) = *(const u16x8*)(VT + prow(dv) * JP + j8);
;     }
;   }
;   glax_z(Z, LR, 0, w2a0, wid, fr, fq);
	ds_read_u16 v73, v10
	ds_read_u16 v57, v10 offset:16384
	ds_read_u16 v71, v10 offset:256
	ds_read_u16 v72, v10 offset:16640
	ds_read_u16 v56, v10 offset:512
	ds_read_u16 v53, v10 offset:16896
	ds_read_u16 v54, v10 offset:768
	ds_read_u16 v55, v10 offset:17152
	ds_read_u16 v52, v10 offset:1024
	ds_read_u16 v49, v10 offset:17408
	ds_read_u16 v50, v10 offset:1280
	ds_read_u16 v51, v10 offset:17664
	ds_read_u16 v48, v10 offset:1536
	ds_read_u16 v45, v10 offset:17920
	ds_read_u16 v46, v10 offset:1792
	ds_read_u16 v47, v10 offset:18176
	ds_read_u16 v44, v10 offset:2048
	ds_read_u16 v41, v10 offset:18432
	ds_read_u16 v42, v10 offset:2304
	ds_read_u16 v43, v10 offset:18688
	ds_read_u16 v40, v10 offset:2560
	ds_read_u16 v37, v10 offset:18944
	ds_read_u16 v38, v10 offset:2816
	ds_read_u16 v39, v10 offset:19200
	ds_read_u16 v36, v10 offset:3072
	ds_read_u16 v33, v10 offset:19456
	ds_read_u16 v34, v10 offset:3328
	ds_read_u16 v35, v10 offset:19712
	ds_read_u16 v32, v10 offset:3584
	ds_read_u16 v29, v10 offset:19968
	ds_read_u16 v30, v10 offset:3840
	ds_read_u16 v31, v10 offset:20224
	v_lshlrev_b32_e32 v10, 2, v15
	v_lshrrev_b32_e32 v11, 1, v15
	v_and_b32_e32 v10, 16, v10
	v_and_b32_e32 v11, 12, v11
	v_and_b32_e32 v12, 0xfffffe3, v15
	v_or3_b32 v10, v12, v10, v11
	v_bfe_u32 v216, v15, 5, 3
	v_lshlrev_b32_e32 v216, 4, v216
	v_xor_b32_e32 v216, v216, v14
	v_mad_u64_u32 v[10:11], s[6:7], v10, s84, v[216:217]
	ds_read_b128 v[10:13], v10 offset:34816
	v_lshlrev_b32_e32 v68, 6, v15
	v_ashrrev_i32_e32 v69, 31, v68
	v_lshl_add_u64 v[68:69], v[68:69], 1, v[66:67]
	v_ashrrev_i32_e32 v15, 3, v21
	s_waitcnt lgkmcnt(0)
	global_store_dwordx4 v[68:69], v[10:13], off
	v_lshlrev_b32_e32 v68, 6, v15
	v_ashrrev_i32_e32 v69, 31, v68
	v_lshlrev_b32_e32 v10, 2, v15
	v_lshrrev_b32_e32 v11, 1, v15
	v_and_b32_e32 v10, 16, v10
	v_and_b32_e32 v11, 12, v11
	v_and_b32_e32 v12, 0xfffffe3, v15
	v_or3_b32 v10, v12, v10, v11
	v_bfe_u32 v216, v15, 5, 3
	v_lshlrev_b32_e32 v216, 4, v216
	v_xor_b32_e32 v216, v216, v14
	v_mad_u64_u32 v[10:11], s[6:7], v10, s84, v[216:217]
	ds_read_b128 v[10:13], v10 offset:34816
	v_lshl_add_u64 v[68:69], v[68:69], 1, v[66:67]
	v_ashrrev_i32_e32 v15, 3, v70
	s_waitcnt lgkmcnt(0)
	global_store_dwordx4 v[68:69], v[10:13], off
	s_nop 1
	v_lshlrev_b32_e32 v10, 2, v15
	v_lshrrev_b32_e32 v11, 1, v15
	v_and_b32_e32 v10, 16, v10
	v_and_b32_e32 v11, 12, v11
	v_and_b32_e32 v12, 0xfffffe3, v15
	v_or3_b32 v10, v12, v10, v11
	v_bfe_u32 v216, v15, 5, 3
	v_lshlrev_b32_e32 v216, 4, v216
	v_xor_b32_e32 v216, v216, v14
	v_mad_u64_u32 v[10:11], s[6:7], v10, s84, v[216:217]
	ds_read_b128 v[10:13], v10 offset:34816
	v_lshlrev_b32_e32 v68, 6, v15
	v_ashrrev_i32_e32 v69, 31, v68
	v_lshl_add_u64 v[68:69], v[68:69], 1, v[66:67]
	v_ashrrev_i32_e32 v15, 3, v74
	s_waitcnt lgkmcnt(0)
	global_store_dwordx4 v[68:69], v[10:13], off
	s_nop 1
	v_lshlrev_b32_e32 v10, 2, v15
	v_lshrrev_b32_e32 v11, 1, v15
	v_and_b32_e32 v10, 16, v10
	v_and_b32_e32 v11, 12, v11
	v_and_b32_e32 v12, 0xfffffe3, v15
	v_or3_b32 v10, v12, v10, v11
	v_bfe_u32 v216, v15, 5, 3
	v_lshlrev_b32_e32 v216, 4, v216
	v_xor_b32_e32 v216, v216, v14
	v_mad_u64_u32 v[10:11], s[6:7], v10, s84, v[216:217]
	ds_read_b128 v[10:13], v10 offset:34816
	v_lshlrev_b32_e32 v14, 6, v15
	v_ashrrev_i32_e32 v15, 31, v14
	v_lshl_add_u64 v[14:15], v[14:15], 1, v[66:67]
	v_cmp_gt_u32_e64 s[6:7], 2, v28
	s_waitcnt lgkmcnt(0)
	global_store_dwordx4 v[14:15], v[10:13], off
	v_mov_b32_e32 v14, 0
	v_mov_b32_e32 v15, 0
	v_lshl_or_b32 v11, v23, 6, v194
	v_mov_b32_e32 v10, 0
	v_add_u32_e32 v105, v11, v20
	v_mov_b32_e32 v12, 0
	v_mov_b32_e32 v13, 0
	s_and_saveexec_b64 s[8:9], s[6:7]
	ds_read_b128 v[12:15], v105
	s_or_b64 exec, exec, s[8:9]
	s_movk_i32 s8, 0xffc0
	s_waitcnt lgkmcnt(0)
	v_mfma_f32_16x16x32_bf16 v[12:15], v[2:5], v[12:15], 0
	v_and_or_b32 v11, v24, s8, v20
	v_add_u32_e32 v66, 0x15400, v11
	s_movk_i32 s8, 0x210
	v_mad_u32_u24 v11, v23, s8, v66
	s_nop 3
	ds_write_b128 v11, v[12:15]
	v_mov_b32_e32 v11, 0
	v_mov_b32_e32 v12, 0
	v_mov_b32_e32 v13, 0
	s_and_saveexec_b64 s[8:9], s[6:7]
	ds_read_b128 v[10:13], v105 offset:1024
	s_or_b64 exec, exec, s[8:9]
	s_waitcnt lgkmcnt(0)
	v_mfma_f32_16x16x32_bf16 v[10:13], v[2:5], v[10:13], 0
	v_mul_u32_u24_e32 v14, 0x210, v23
	v_add_u32_e32 v106, v66, v14
	v_mov_b32_e32 v14, 0
	v_mov_b32_e32 v15, 0
	s_nop 3
	ds_write_b128 v106, v[10:13] offset:8448
	v_mov_b32_e32 v10, 0
	v_mov_b32_e32 v12, 0
	v_mov_b32_e32 v13, 0
	s_and_saveexec_b64 s[8:9], s[6:7]
	ds_read_b128 v[12:15], v105 offset:2048
	s_or_b64 exec, exec, s[8:9]
	s_waitcnt lgkmcnt(0)
	v_mfma_f32_16x16x32_bf16 v[12:15], v[2:5], v[12:15], 0
	s_lshl_b32 s56, s67, 8
	v_mov_b32_e32 v11, 0
	s_nop 5
	ds_write_b128 v106, v[12:15] offset:16896
	v_mov_b32_e32 v12, 0
	v_mov_b32_e32 v13, 0
	s_and_saveexec_b64 s[8:9], s[6:7]
	ds_read_b128 v[10:13], v105 offset:3072
	s_or_b64 exec, exec, s[8:9]
	s_waitcnt lgkmcnt(0)
; __device__ __forceinline__ void glax_item(char* shm, const Params& P, int l, int cgi, int hd, bf16x8 w2a0, bf16x8 w2a1,
;                                           float bias0, float bias1) {
;     ...
;       float gt0 = GT[dk], gt1 = GT[128 + dk], gt2 = GT[256 + dk], gt3 = GT[384 + dk];
;       float blast = gt0 + gt1 + gt2 + gt3;
;       float off;
;       if (!dir) off = (rg > 0 ? gt0 : 0.f) + (rg > 1 ? gt1 : 0.f) + (rg > 2 ? gt2 : 0.f);
;       else off = (rg < 3 ? gt3 : 0.f) + (rg < 2 ? gt2 : 0.f) + (rg < 1 ? gt1 : 0.f);
;       if (dir == 0) glax_z(Z, LR, 1, w2a1, wid, fr, fq);
;       const float eblast = __expf(blast);
;       u16x8 kd0, kd1;
; #pragma unroll
;       for (int rr = 0; rr < 16; ++rr) {
;         float b = g[rr] + off;
;         float eb = __expf(b), enb = __builtin_amdgcn_rcpf(eb), ed = eblast * enb;
;         float qv = bf2f(qraw[rr]), kv = bf2f(kraw[rr]);
;         int row = rg * 16 + rr;
;         Q[row * QP + dk] = f2bf(qv * qscale * eb);
;         Kt[row * QP + dk] = f2bf(kv * enb);
;         u16 kd = f2bf(kv * ed);
;         if (rr < 8) kd0[rr] = kd; else kd1[rr - 8] = kd;
;       }
;       *(u16x8*)(img + 16384 + lds_byte_g<2>(dk, rg * 16)) = kd0;
;       *(u16x8*)(img + 16384 + lds_byte_g<2>(dk, rg * 16 + 8)) = kd1;
;       if (rg == 0) ((float*)(img + 32768))[dk] = eblast;
;     }
;     __syncthreads();
; #pragma unroll
;     for (int k = 0; k < 2; ++k) {
;       int u = tid + k * 512, row = u >> 4, kb = (u >> 2) & 3, f4 = u & 3;
;       u16x4 lo = *(const u16x4*)(Q + row * QP + kb * 32 + f4 * 4);
;       u16x4 hi = *(const u16x4*)(Q + row * QP + kb * 32 + 16 + f4 * 4);
;       u16x8 w;
;       w[0] = lo[0]; w[1] = lo[1]; w[2] = lo[2]; w[3] = lo[3]; w[4] = hi[0]; w[5] = hi[1]; w[6] = hi[2]; w[7] = hi[3];
;       *(u16x8*)(img + lds_byte_g<4>(row, kb * 32 + f4 * 8)) = w;
;     }
;     {
;       const int ti = wid >> 1, tj0 = (wid & 1) * 2;
;       bf16x8 qf[4];
; #pragma unroll
;       for (int ks = 0; ks < 4; ++ks) qf[ks] = *(const bf16x8*)(Q + (ti * 16 + fr) * QP + ks * 32 + fq * 8);
; #pragma unroll
;       for (int jj = 0; jj < 2; ++jj) {
;         f32x4 sc = f32x4{0.f, 0.f, 0.f, 0.f};
; #pragma unroll
;         for (int ks = 0; ks < 4; ++ks) {
;           bf16x8 kf = *(const bf16x8*)(Kt + ((tj0 + jj) * 16 + fr) * QP + ks * 32 + fq * 8);
;           sc = __builtin_amdgcn_mfma_f32_16x16x32_bf16(kf, qf[ks], sc, 0, 0, 0);
	v_mfma_f32_16x16x32_bf16 v[10:13], v[2:5], v[10:13], 0
	v_lshlrev_b32_e32 v15, 6, v16
	v_and_b32_e32 v15, 0x3c0, v15
	v_lshlrev_b32_e32 v66, 5, v26
	v_and_or_b32 v15, v66, 32, v15
	v_ashrrev_i32_e32 v14, 6, v24
	s_nop 2
	ds_write_b128 v106, v[10:13] offset:25344
	v_lshrrev_b32_e32 v11, 3, v24
	v_lshlrev_b32_e32 v10, 2, v16
	v_and_b32_e32 v11, 14, v11
	v_lshrrev_b32_e32 v13, 8, v24
	v_lshlrev_b32_e32 v12, 4, v26
	v_or_b32_e32 v102, 0x15400, v10
	v_or_b32_e32 v107, 0x14c00, v10
	v_add_lshl_u32 v11, v11, v13, 10
	v_and_b32_e32 v10, 32, v10
	v_or_b32_e32 v13, 16, v15
	s_movk_i32 s8, 0x80
	s_movk_i32 s22, 0x2100
	v_bitop3_b32 v66, v15, v11, v10 bitop3:0xde
	v_bitop3_b32 v68, v13, v11, v10 bitop3:0xde
	v_cmp_gt_u32_e64 s[8:9], s8, v24
	v_and_b32_e32 v13, 0xc0, v27
	v_lshlrev_b32_e32 v10, 1, v14
	v_or_b32_e32 v27, v12, v23
	v_lshl_add_u32 v108, v24, 2, v195
	v_mul_lo_u32 v24, v26, s22
	v_or_b32_e32 v12, 1, v12
	s_movk_i32 s22, 0x210
	v_lshrrev_b32_e32 v15, 5, v25
	v_and_b32_e32 v25, 2, v10
	v_mul_lo_u32 v10, v27, s84
	v_lshlrev_b32_e32 v11, 3, v28
	s_mov_b32 s11, 0x11800
	v_mul_lo_u32 v141, v12, s22
	s_movk_i32 s22, 0x880
	v_lshlrev_b32_e32 v94, 2, v28
	v_add3_u32 v28, v10, v11, s11
	v_or_b32_e32 v70, s10, v23
	v_cmp_gt_i32_e64 s[10:11], 3, v26
	v_cmp_gt_i32_e64 s[12:13], 2, v26
	v_cmp_gt_i32_e64 s[14:15], 1, v26
	v_cmp_lt_i32_e64 s[16:17], 0, v26
	v_cmp_lt_i32_e64 s[18:19], 1, v26
	v_cmp_lt_i32_e64 s[20:21], 2, v26
	v_mul_lo_u32 v26, v26, s22
	v_mad_u64_u32 v[74:75], s[22:23], v12, s85, v[18:19]
	v_lshlrev_b32_e32 v12, 16, v56
	v_mul_f32_e32 v75, 0x3db504f3, v12
	v_lshlrev_b32_e32 v12, 16, v54
	v_mul_f32_e32 v113, 0x3db504f3, v12
	v_lshlrev_b32_e32 v12, 16, v52
	v_mul_f32_e32 v115, 0x3db504f3, v12
	v_lshlrev_b32_e32 v12, 16, v50
	v_mul_f32_e32 v117, 0x3db504f3, v12
	v_lshlrev_b32_e32 v12, 16, v48
	v_mul_f32_e32 v119, 0x3db504f3, v12
	v_lshlrev_b32_e32 v12, 16, v46
	v_mul_f32_e32 v121, 0x3db504f3, v12
	v_lshlrev_b32_e32 v12, 16, v44
	v_mul_f32_e32 v123, 0x3db504f3, v12
	v_lshlrev_b32_e32 v12, 16, v42
	v_mul_f32_e32 v125, 0x3db504f3, v12
	v_lshlrev_b32_e32 v12, 16, v40
	v_mul_f32_e32 v127, 0x3db504f3, v12
	v_lshlrev_b32_e32 v12, 16, v38
	v_mul_f32_e32 v129, 0x3db504f3, v12
	v_lshlrev_b32_e32 v12, 16, v36
	v_mul_f32_e32 v131, 0x3db504f3, v12
	v_lshlrev_b32_e32 v12, 16, v34
	v_mul_f32_e32 v133, 0x3db504f3, v12
	v_lshlrev_b32_e32 v12, 16, v32
	v_mul_f32_e32 v135, 0x3db504f3, v12
	v_lshlrev_b32_e32 v12, 16, v30
	v_mul_f32_e32 v137, 0x3db504f3, v12
	v_mul_lo_u32 v12, v19, s85
	v_and_b32_e32 v18, 24, v22
	s_mov_b32 s23, 0x3ffffc
	v_and_b32_e32 v0, 48, v0
	v_lshlrev_b32_e32 v10, 5, v14
	v_add3_u32 v139, v13, v12, v18
	v_and_or_b32 v12, v14, s23, v15
	v_lshlrev_b32_e32 v14, 6, v19
	s_movk_i32 s22, 0x3c0
	v_lshlrev_b32_e32 v19, 2, v19
	v_and_or_b32 v14, v14, s22, v0
	v_lshlrev_b32_e32 v12, 10, v12
	v_and_b32_e32 v19, 32, v19
	v_bitop3_b32 v90, v14, v12, v19 bitop3:0xde
	v_mul_lo_u32 v12, v17, s85
	v_add3_u32 v140, v13, v12, v18
	v_lshrrev_b32_e32 v12, 6, v21
	v_lshlrev_b32_e32 v13, 6, v17
	v_and_or_b32 v12, v12, s23, v15
	v_and_or_b32 v0, v13, s22, v0
	v_lshlrev_b32_e32 v13, 2, v17
	v_lshlrev_b32_e32 v12, 10, v12
	v_and_b32_e32 v13, 32, v13
	v_bitop3_b32 v92, v0, v12, v13 bitop3:0xde
	v_lshlrev_b32_e32 v0, 4, v25
	v_or_b32_e32 v12, v0, v23
	v_or_b32_e32 v0, v0, v94
	v_mul_u32_u24_e32 v17, 0x110, v12
	v_or_b32_e32 v12, 1, v0
	v_cmp_ge_i32_e64 s[22:23], v0, v27
	v_cmp_le_i32_e64 s[24:25], v0, v27
	v_cmp_ge_i32_e64 s[26:27], v12, v27
	v_cmp_lt_i32_e64 s[28:29], v0, v27
	v_or_b32_e32 v12, 2, v0
	v_or_b32_e32 v0, 3, v0
	v_cmp_ge_i32_e64 s[36:37], v0, v27
	v_cmp_le_i32_e64 s[38:39], v0, v27
	v_or_b32_e32 v0, 1, v25
	v_cmp_ge_i32_e64 s[30:31], v12, v27
	v_cmp_le_i32_e64 s[34:35], v12, v27
	v_lshlrev_b32_e32 v12, 4, v0
	s_lshl_b32 s56, s56, 1
	v_readlane_b32 s60, v248, 0
	v_or_b32_e32 v13, v12, v23
	v_or_b32_e32 v12, v12, v94
	v_readlane_b32 s61, v248, 1
	s_add_u32 s56, s60, s56
	v_ashrrev_i32_e32 v11, 31, v10
	v_or_b32_e32 v26, v26, v16
	v_lshlrev_b32_e32 v22, 5, v25
; __device__ __forceinline__ void glax_item(char* shm, const Params& P, int l, int cgi, int hd, bf16x8 w2a0, bf16x8 w2a1,
;                                           float bias0, float bias1) {
;     ...
;   f32x4 osum[4][2];
; #pragma unroll
;   for (int it = 0; it < 4; ++it)
; #pragma unroll
;     for (int d = 0; d < 2; ++d) osum[it][d] = f32x4{0.f, 0.f, 0.f, 0.f};
; #pragma unroll 1
;   for (int dir = 0; dir < 2; ++dir) {
;     char* img = P.img + ((long)(dir * NCH + cgi) * 4 + hd) * IMG_B;
;     ...
;       bf16x8 vf[2][2];
; #pragma unroll
;       for (int d = 0; d < 2; ++d)
; #pragma unroll
;         for (int k2 = 0; k2 < 2; ++k2) vf[d][k2] = *(const bf16x8*)(VT + ((2 * wid + d) * 16 + fr) * JP + k2 * 32 + fq * 8);
	v_mul_u32_u24_e32 v25, 0x110, v13
	v_or_b32_e32 v13, 1, v12
	v_or_b32_e32 v14, 16, v70
	v_or_b32_e32 v18, 32, v70
	s_addc_u32 s57, s61, 0
	v_or_b32_e32 v95, v10, v23
	v_lshlrev_b32_e32 v110, 1, v26
	v_lshlrev_b32_e32 v26, 16, v71
	v_cmp_ge_i32_e64 s[40:41], v12, v27
	v_cmp_le_i32_e64 s[42:43], v12, v27
	v_cmp_ge_i32_e64 s[44:45], v13, v27
	v_cmp_lt_i32_e64 s[46:47], v12, v27
	v_or_b32_e32 v13, 2, v12
	v_or_b32_e32 v12, 3, v12
	v_ashrrev_i32_e32 v71, 31, v70
	v_ashrrev_i32_e32 v15, 31, v14
	v_ashrrev_i32_e32 v19, 31, v18
	v_lshl_add_u64 v[10:11], v[10:11], 1, s[56:57]
	v_mov_b32_e32 v21, v1
	v_mul_lo_u32 v103, v27, s85
	v_or_b32_e32 v148, 0x11800, v20
	v_lshlrev_b32_e32 v73, 16, v73
	v_mul_f32_e32 v111, 0x3db504f3, v26
	v_cmp_ge_i32_e64 s[48:49], v13, v27
	v_cmp_le_i32_e64 s[50:51], v13, v27
	v_cmp_ge_i32_e64 s[52:53], v12, v27
	v_cmp_le_i32_e64 s[54:55], v12, v27
	v_lshlrev_b32_e32 v26, 5, v0
	v_mul_lo_u32 v27, v95, s84
	v_mul_u32_u24_e32 v23, 0x90, v23
	v_lshlrev_b64 v[12:13], 11, v[70:71]
	v_lshlrev_b64 v[14:15], 11, v[14:15]
	v_lshlrev_b64 v[18:19], 11, v[18:19]
	v_lshl_add_u64 v[94:95], v[10:11], 0, v[20:21]
	v_mov_b32_e32 v10, 0
	s_mov_b32 s58, 0
	v_ashrrev_i32_e32 v67, 31, v66
	v_ashrrev_i32_e32 v69, 31, v68
	v_mul_f32_e32 v109, 0x3db504f3, v73
	v_lshlrev_b32_e32 v73, 16, v72
	v_lshlrev_b32_e32 v72, 16, v57
	v_add_u32_e32 v112, 0x110, v74
	v_lshlrev_b32_e32 v77, 16, v55
	v_lshlrev_b32_e32 v76, 16, v53
	v_add_u32_e32 v114, 0x220, v74
	v_add_u32_e32 v116, 0x330, v74
	v_lshlrev_b32_e32 v79, 16, v51
	v_lshlrev_b32_e32 v78, 16, v49
	v_add_u32_e32 v118, 0x440, v74
	v_add_u32_e32 v120, 0x550, v74
	v_lshlrev_b32_e32 v81, 16, v47
	v_lshlrev_b32_e32 v80, 16, v45
	v_add_u32_e32 v122, 0x660, v74
	v_add_u32_e32 v124, 0x770, v74
	v_lshlrev_b32_e32 v83, 16, v43
	v_lshlrev_b32_e32 v82, 16, v41
	v_add_u32_e32 v126, 0x880, v74
	v_add_u32_e32 v128, 0x990, v74
	v_lshlrev_b32_e32 v85, 16, v39
	v_lshlrev_b32_e32 v84, 16, v37
	v_add_u32_e32 v130, 0xaa0, v74
	v_add_u32_e32 v132, 0xbb0, v74
	v_lshlrev_b32_e32 v87, 16, v35
	v_lshlrev_b32_e32 v86, 16, v33
	v_add_u32_e32 v134, 0xcc0, v74
	v_add_u32_e32 v136, 0xdd0, v74
	v_lshlrev_b32_e32 v89, 16, v31
	v_lshlrev_b32_e32 v88, 16, v29
	v_add_u32_e32 v138, 0xee0, v74
	v_ashrrev_i32_e32 v91, 31, v90
	v_ashrrev_i32_e32 v93, 31, v92
	v_lshl_add_u64 v[96:97], v[94:95], 0, v[12:13]
	v_lshl_add_u64 v[98:99], v[94:95], 0, v[14:15]
	v_lshl_add_u64 v[100:101], v[94:95], 0, v[18:19]
	s_mov_b64 s[84:85], -1
	v_add_u32_e32 v71, v102, v24
	v_add_u32_e32 v141, v102, v141
	v_lshlrev_b32_e32 v0, 2, v16
	v_add_u32_e32 v142, v103, v20
	v_add_u32_e32 v143, v20, v17
	v_add_u32_e32 v144, v28, v22
	v_add_u32_e32 v145, v20, v25
	v_add_u32_e32 v146, v28, v26
	v_lshrrev_b32_e32 v216, 4, v182
	v_lshrrev_b32_e32 v217, 6, v182
	v_xor_b32_e32 v216, v216, v217
	v_and_b32_e32 v216, 3, v216
	v_bfe_u32 v217, v182, 8, 1
	v_lshl_add_u32 v216, v217, 2, v216
	v_lshl_add_u32 v147, v216, 4, v27
	v_xor_b32_e32 v216, 4, v216
	v_lshl_add_u32 v218, v216, 4, v27
	v_add_u32_e32 v148, v148, v23
	v_mov_b32_e32 v11, v10
	v_mov_b32_e32 v12, v10
	v_mov_b32_e32 v13, v10
	v_mov_b32_e32 v14, v10
	v_mov_b32_e32 v15, v10
	v_mov_b32_e32 v16, v10
	v_mov_b32_e32 v17, v10
	v_mov_b32_e32 v18, v10
	v_mov_b32_e32 v19, v10
	v_mov_b32_e32 v20, v10
	v_mov_b32_e32 v21, v10
	v_mov_b32_e32 v22, v10
	v_mov_b32_e32 v23, v10
	v_mov_b32_e32 v24, v10
	v_mov_b32_e32 v25, v10
	v_mov_b32_e32 v26, v10
	v_mov_b32_e32 v27, v10
	v_mov_b32_e32 v28, v10
	v_mov_b32_e32 v29, v10
	v_mov_b32_e32 v34, v10
	v_mov_b32_e32 v35, v10
	v_mov_b32_e32 v36, v10
	v_mov_b32_e32 v37, v10
	v_mov_b32_e32 v30, v10
	v_mov_b32_e32 v31, v10
	v_mov_b32_e32 v32, v10
	v_mov_b32_e32 v33, v10
	v_mov_b32_e32 v38, v10
	v_mov_b32_e32 v39, v10
	v_mov_b32_e32 v40, v10
	v_mov_b32_e32 v41, v10
	s_waitcnt lgkmcnt(0)
	s_barrier
	s_branch .LBB0_357
	s_nop 0
	s_nop 0
	s_nop 0
	s_nop 0
	s_nop 0
	s_nop 0
	s_nop 0
	s_nop 0
	s_nop 0
	s_nop 0
	s_nop 0
	s_nop 0
	s_nop 0
	s_nop 0
	s_nop 0
	s_nop 0
	s_nop 0
	s_nop 0
	s_nop 0

; __device__ __forceinline__ void glax_item(char* shm, const Params& P, int l, int cgi, int hd, bf16x8 w2a0, bf16x8 w2a1,
;                                           float bias0, float bias1) {
;     ...
; #pragma unroll
;     for (int k = 0; k < 2; ++k) {
;       int u = tid + k * 512, row = u >> 4, kb = (u >> 2) & 3, f4 = u & 3;
;       u16x4 lo = *(const u16x4*)(Q + row * QP + kb * 32 + f4 * 4);
;       u16x4 hi = *(const u16x4*)(Q + row * QP + kb * 32 + 16 + f4 * 4);
;       u16x8 w;
;       w[0] = lo[0]; w[1] = lo[1]; w[2] = lo[2]; w[3] = lo[3]; w[4] = hi[0]; w[5] = hi[1]; w[6] = hi[2]; w[7] = hi[3];
;       *(u16x8*)(img + lds_byte_g<4>(row, kb * 32 + f4 * 8)) = w;
;     }
;     {
;       const int ti = wid >> 1, tj0 = (wid & 1) * 2;
;       bf16x8 qf[4];
; #pragma unroll
;       for (int ks = 0; ks < 4; ++ks) qf[ks] = *(const bf16x8*)(Q + (ti * 16 + fr) * QP + ks * 32 + fq * 8);
; #pragma unroll
;       for (int jj = 0; jj < 2; ++jj) {
;         f32x4 sc = f32x4{0.f, 0.f, 0.f, 0.f};
; #pragma unroll
;         for (int ks = 0; ks < 4; ++ks) {
;           bf16x8 kf = *(const bf16x8*)(Kt + ((tj0 + jj) * 16 + fr) * QP + ks * 32 + fq * 8);
;           sc = __builtin_amdgcn_mfma_f32_16x16x32_bf16(kf, qf[ks], sc, 0, 0, 0);
;         }
;         const int i = ti * 16 + fr;
;         u16x4 pv;
; #pragma unroll
;         for (int e = 0; e < 4; ++e) {
;           int j = (tj0 + jj) * 16 + fq * 4 + e;
;           bool keep = dir ? (j >= i) : (j <= i);
;           pv[e] = keep ? f2bf(sc[e]) : (u16)0;
;         }
;         *(u16x4*)(Pm + i * JP + (tj0 + jj) * 16 + fq * 4) = pv;
;       }
;     }
;     __syncthreads();
;     {
;       bf16x8 vf[2][2];
; #pragma unroll
;       for (int d = 0; d < 2; ++d)
; #pragma unroll
;         for (int k2 = 0; k2 < 2; ++k2) vf[d][k2] = *(const bf16x8*)(VT + ((2 * wid + d) * 16 + fr) * JP + k2 * 32 + fq * 8);
; #pragma unroll
;       for (int it = 0; it < 4; ++it) {
;         bf16x8 pf[2];
; #pragma unroll
;         for (int k2 = 0; k2 < 2; ++k2) pf[k2] = *(const bf16x8*)(Pm + (it * 16 + fr) * JP + k2 * 32 + fq * 8);
; #pragma unroll
;         for (int d = 0; d < 2; ++d) {
;           f32x4 a = osum[it][d];
; #pragma unroll
;           for (int k2 = 0; k2 < 2; ++k2) a = __builtin_amdgcn_mfma_f32_16x16x32_bf16(vf[d][k2], pf[k2], a, 0, 0, 0);
;           osum[it][d] = a;
;         }
;         if (dir) {
;           u16x8 ov;
; #pragma unroll
.LBB0_377:
	s_or_b64 exec, exec, s[62:63]
	s_waitcnt lgkmcnt(0)
	s_barrier
	ds_read2_b64 v[42:45], v139 offset1:4
	v_lshl_add_u64 v[46:47], s[56:57], 0, v[90:91]
	v_cndmask_b32_e64 v102, 0, 1, s[24:25]
	v_cndmask_b32_e64 v103, 0, 1, s[22:23]
	v_cndmask_b32_e64 v102, v103, v102, s[84:85]
	s_waitcnt lgkmcnt(0)
	global_store_dwordx4 v[46:47], v[42:45], off
	ds_read2_b64 v[42:45], v140 offset1:4
	v_lshl_add_u64 v[46:47], s[56:57], 0, v[92:93]
	v_cndmask_b32_e64 v103, 0, 1, s[28:29]
	v_cndmask_b32_e64 v149, 0, 1, s[26:27]
	v_and_b32_e32 v102, 1, v102
	s_waitcnt lgkmcnt(0)
	global_store_dwordx4 v[46:47], v[42:45], off
	ds_read_b128 v[42:45], v142
	ds_read_b128 v[46:49], v142 offset:64
	ds_read_b128 v[50:53], v142 offset:128
	ds_read_b128 v[54:57], v142 offset:192
	ds_read_b128 v[150:153], v143 offset:17408
	ds_read_b128 v[154:157], v143 offset:17472
	s_waitcnt lgkmcnt(0)
	v_mfma_f32_16x16x32_bf16 v[150:153], v[150:153], v[42:45], 0
	v_cndmask_b32_e64 v103, v149, v103, s[84:85]
	v_cmp_eq_u32_e32 vcc, 1, v102
	v_and_b32_e32 v103, 1, v103
	v_mfma_f32_16x16x32_bf16 v[150:153], v[154:157], v[46:49], v[150:153]
	ds_read_b128 v[154:157], v143 offset:17536
	s_waitcnt lgkmcnt(0)
	v_mfma_f32_16x16x32_bf16 v[150:153], v[154:157], v[50:53], v[150:153]
	ds_read_b128 v[154:157], v143 offset:17600
	s_waitcnt lgkmcnt(0)
	v_mfma_f32_16x16x32_bf16 v[150:153], v[154:157], v[54:57], v[150:153]
	s_nop 7
	v_cvt_pk_bf16_f32 v102, v150, s0
	v_cndmask_b32_e32 v102, 0, v102, vcc
	v_cmp_eq_u32_e32 vcc, 1, v103
	v_cvt_pk_bf16_f32 v103, v151, s0
	v_cndmask_b32_e64 v150, 0, 1, s[30:31]
	v_cndmask_b32_e32 v149, 0, v103, vcc
	v_cndmask_b32_e64 v103, 0, 1, s[34:35]
	v_cndmask_b32_e64 v103, v150, v103, s[84:85]
	v_cndmask_b32_e64 v150, 0, 1, s[38:39]
	v_cndmask_b32_e64 v151, 0, 1, s[36:37]
	v_and_b32_e32 v103, 1, v103
	v_cndmask_b32_e64 v150, v151, v150, s[84:85]
	v_cmp_eq_u32_e32 vcc, 1, v103
	v_cvt_pk_bf16_f32 v103, v152, s0
	v_and_b32_e32 v150, 1, v150
	v_cndmask_b32_e32 v103, 0, v103, vcc
	v_cmp_eq_u32_e32 vcc, 1, v150
	v_cvt_pk_bf16_f32 v150, v153, s0
	v_perm_b32 v102, v149, v102, s74
	v_cndmask_b32_e32 v150, 0, v150, vcc
	v_perm_b32 v103, v150, v103, s74
	ds_write_b64 v144, v[102:103]
	ds_read_b128 v[150:153], v145 offset:17408
	s_waitcnt lgkmcnt(0)
	v_mfma_f32_16x16x32_bf16 v[42:45], v[150:153], v[42:45], 0
	ds_read_b128 v[150:153], v145 offset:17472
	v_cndmask_b32_e64 v102, 0, 1, s[60:61]
	v_cmp_ne_u32_e64 s[56:57], 1, v102
	s_waitcnt lgkmcnt(0)
	v_mfma_f32_16x16x32_bf16 v[42:45], v[150:153], v[46:49], v[42:45]
	ds_read_b128 v[46:49], v145 offset:17536
	s_waitcnt lgkmcnt(0)
	v_mfma_f32_16x16x32_bf16 v[42:45], v[46:49], v[50:53], v[42:45]
	ds_read_b128 v[46:49], v145 offset:17600
	s_waitcnt lgkmcnt(0)
	v_mfma_f32_16x16x32_bf16 v[42:45], v[46:49], v[54:57], v[42:45]
	v_cndmask_b32_e64 v46, 0, 1, s[42:43]
	v_cndmask_b32_e64 v47, 0, 1, s[40:41]
	v_cndmask_b32_e64 v46, v47, v46, s[84:85]
	v_and_b32_e32 v46, 1, v46
	v_cmp_eq_u32_e32 vcc, 1, v46
	v_cndmask_b32_e64 v46, 0, 1, s[46:47]
	v_cndmask_b32_e64 v47, 0, 1, s[44:45]
	v_cndmask_b32_e64 v46, v47, v46, s[84:85]
	v_cvt_pk_bf16_f32 v42, v42, s0
	v_and_b32_e32 v46, 1, v46
	v_cndmask_b32_e32 v42, 0, v42, vcc
	v_cmp_eq_u32_e32 vcc, 1, v46
	v_cvt_pk_bf16_f32 v43, v43, s0
	v_cndmask_b32_e64 v47, 0, 1, s[48:49]
	v_cndmask_b32_e32 v46, 0, v43, vcc
	v_cndmask_b32_e64 v43, 0, 1, s[50:51]
	v_cndmask_b32_e64 v43, v47, v43, s[84:85]
	v_and_b32_e32 v43, 1, v43
	v_cmp_eq_u32_e32 vcc, 1, v43
	v_cvt_pk_bf16_f32 v43, v44, s0
	v_cndmask_b32_e64 v44, 0, 1, s[54:55]
	v_cndmask_b32_e64 v47, 0, 1, s[52:53]
	v_cndmask_b32_e64 v44, v47, v44, s[84:85]
	v_and_b32_e32 v44, 1, v44
	v_cndmask_b32_e32 v43, 0, v43, vcc
	v_cmp_eq_u32_e32 vcc, 1, v44
	v_cvt_pk_bf16_f32 v44, v45, s0
	v_perm_b32 v42, v46, v42, s74
	v_cndmask_b32_e32 v44, 0, v44, vcc
	v_perm_b32 v43, v44, v43, s74
	ds_write_b64 v146, v[42:43]
	s_waitcnt lgkmcnt(0)
	s_barrier
	ds_read_b128 v[54:57], v147 offset:34816
	ds_read_b128 v[46:49], v218 offset:34816
	ds_read_b128 v[50:53], v147 offset:37120
	ds_read_b128 v[42:45], v218 offset:37120
	ds_read_b128 v[150:153], v148
	ds_read_b128 v[154:157], v148 offset:64
	s_waitcnt lgkmcnt(0)
	v_mfma_f32_16x16x32_bf16 v[10:13], v[54:57], v[150:153], v[10:13]
	s_andn2_b64 vcc, exec, s[60:61]
	v_mfma_f32_16x16x32_bf16 v[14:17], v[50:53], v[150:153], v[14:17]
	v_mfma_f32_16x16x32_bf16 v[10:13], v[46:49], v[154:157], v[10:13]
	v_mfma_f32_16x16x32_bf16 v[14:17], v[42:45], v[154:157], v[14:17]
	s_cbranch_vccnz .LBB0_379
	s_nop 6
	v_cvt_pk_bf16_f32 v153, v16, v17
	v_cvt_pk_bf16_f32 v152, v14, v15
	v_cvt_pk_bf16_f32 v151, v12, v13
	v_cvt_pk_bf16_f32 v150, v10, v11
	global_store_dwordx4 v[96:97], v[150:153], off
